# M unit: conv taps / weights / gate values requested at the top of the unit (no serialized exec-masked loads in the tail)
# baseline (speedup 1.0000x reference)
; DI unsigned cvtpk(float lo, float hi) { f32x2_t v = {lo, hi}; bf16x2_t b = __builtin_convertvector(v, bf16x2_t); return __builtin_bit_cast(unsigned, b); }
; DI void unit_sample_mem(int u, const bf16* __restrict__ MQ, const float* __restrict__ cmk, const float* __restrict__ cmv, const bf16* __restrict__ G, bf16* __restrict__ MIX, const bf16* __restrict__ CB, const bf16* __restrict__ U, const float* __restrict__ cconv, const float* __restrict__ convw, ...
;     ...
;     {   const int jj = tid >> 7, c = hh * 128 + (tid & 127); const size_t srow = (size_t)(MP + b * 4 + jj);
;         const float f0 = (jj >= 2) ? bflo((unsigned)U[(srow - 2) * 256 + c]) : cconv[((size_t)b * 2 + jj) * 256 + c];
;         const float f1 = (jj >= 1) ? bflo((unsigned)U[(srow - 1) * 256 + c]) : cconv[((size_t)b * 2 + 1) * 256 + c];
;         const float f2 = bflo((unsigned)U[srow * 256 + c]);
;         const float val = bflo((unsigned)CB[srow * 256 + c]) * (convw[c] * f0 + convw[256 + c] * f1 + convw[512 + c] * f2) * bflo((unsigned)G[srow * D + c]);
;         MIX[srow * D + c] = (bf16)(cvtpk(val, 0.f) & 0xffffu); }
; __global__ void __launch_bounds__(NT, 2) fwd(Args args) {
;     ...
;         for (int r2 = 0; r2 < ((SEQ_P2A & 8) ? 2 : 1); ++r2) for (;;) { const int u = __builtin_amdgcn_readfirstlane(q_next(ctl + CW_Q0 + (pass * 8 + 6 + r2) * 64, slot, tid)); if (u >= 256) break;
;             unit_sample_mem(u, MQB, args.in[6], args.in[7], GB, MIX, CB, UB, args.in[5], args.in[10], lds, tid, lane, wave); }
.LBB0_828:
	s_add_u32 s0, s22, 0x7400
	s_addc_u32 s1, s23, 0
	s_add_i32 s31, 0, 0x20180
	v_and_b32_e32 v2, 64, v1
	s_lshl_b32 s30, s33, 3
	v_mov_b32_e32 v131, 0
	v_mov_b32_e32 v145, s31
	s_mov_b64 s[4:5], 0x4000
	s_mov_b64 s[6:7], 0x8000
	s_mov_b64 s[8:9], 0xc000
	s_mov_b64 s[10:11], 0x10000
	s_mov_b64 s[12:13], 0x14000
	s_mov_b64 s[14:15], 0x18000
	s_mov_b64 s[16:17], 0x1c000
	s_mov_b64 s[18:19], 0x20000
	s_mov_b64 s[20:21], 0x24000
	s_mov_b64 s[22:23], 0x28000
	s_mov_b64 s[26:27], 0x2c000
	s_mov_b64 s[28:29], 0x30000
	s_mov_b64 s[34:35], 0x34000
	s_mov_b64 s[38:39], 0x38000
	s_mov_b64 s[42:43], 0x3c000
	s_mov_b32 s40, 0x800000
	s_mov_b32 s41, 0xf149f2ca
	s_movk_i32 s44, 0x300
	v_xor_b32_e32 v147, 1, v1
	v_add_u32_e32 v149, 64, v2
	v_xor_b32_e32 v151, 2, v1
	v_xor_b32_e32 v153, 4, v1
	v_xor_b32_e32 v155, 8, v1
	s_branch .LBB0_831
.LBB0_830:
	s_and_b64 vcc, exec, s[2:3]
	s_cbranch_vccnz .LBB0_852

; DI void unit_sample_mem(int u, const bf16* __restrict__ MQ, const float* __restrict__ cmk, const float* __restrict__ cmv, const bf16* __restrict__ G, bf16* __restrict__ MIX, const bf16* __restrict__ CB, const bf16* __restrict__ U, const float* __restrict__ cconv, const float* __restrict__ convw, ...
;     asm volatile("" : "+v"(lane), "+v"(tid));
;     const int b = u >> 1, hh = u & 1, half = lane >> 5, l32 = lane & 31, hd = (lane >> 4) & 1, coff = hh * 128 + l32 * 4;
;     const float* mk = cmk + (size_t)b * 256 * 256 + coff; const float* mv = cmv + (size_t)b * 256 * 256 + coff;
;     f32x4 kv[16], vv[16];
; #pragma unroll
;     for (int i = 0; i < 16; ++i) { const int mi = wave + 8 * (2 * i + half); kv[i] = __builtin_nontemporal_load((const f32x4*)(mk + (size_t)mi * 256)); vv[i] = __builtin_nontemporal_load((const f32x4*)(mv + (size_t)mi * 256)); }
;     ...
;     {   const int jj = tid >> 7, c = hh * 128 + (tid & 127); const size_t srow = (size_t)(MP + b * 4 + jj);
;         const float f0 = (jj >= 2) ? bflo((unsigned)U[(srow - 2) * 256 + c]) : cconv[((size_t)b * 2 + jj) * 256 + c];
;         const float f1 = (jj >= 1) ? bflo((unsigned)U[(srow - 1) * 256 + c]) : cconv[((size_t)b * 2 + 1) * 256 + c];
;         const float f2 = bflo((unsigned)U[srow * 256 + c]);
;         const float val = bflo((unsigned)CB[srow * 256 + c]) * (convw[c] * f0 + convw[256 + c] * f1 + convw[512 + c] * f2) * bflo((unsigned)G[srow * D + c]);
.LBB0_835:
	s_or_b64 exec, exec, s[2:3]
	s_waitcnt lgkmcnt(0)
	s_barrier
	ds_read_b32 v2, v145
	s_mov_b64 s[2:3], -1
	s_waitcnt lgkmcnt(0)
	v_readfirstlane_b32 s45, v2
	s_cmpk_gt_i32 s45, 0xff
	s_cbranch_scc1 .LBB0_830
	s_ashr_i32 s48, s45, 1
	s_lshl_b32 s2, s45, 7
	s_ashr_i32 s49, s48, 31
	v_readlane_b32 s52, v247, 2
	v_mov_b32_e32 v144, v182
	v_mov_b32_e32 v157, v0
	s_and_b32 s45, s2, 0x80
	v_ashrrev_i32_e32 v188, 7, v0
	v_and_b32_e32 v189, 0x7f, v0
	v_or_b32_e32 v189, s45, v189
	s_lshl_b32 s50, s48, 2
	s_add_i32 s50, s50, 0x4000
	v_add_u32_e32 v190, s50, v188
	v_lshlrev_b32_e32 v191, 1, v189
	v_lshl_add_u32 v192, v190, 9, v191
	v_lshl_add_u32 v193, v190, 11, v191
	v_lshlrev_b32_e32 v194, 2, v189
	v_min_u32_e32 v195, 1, v188
	v_lshl_add_u32 v195, v195, 10, v194
	v_readlane_b32 s50, v247, 12
	v_readlane_b32 s51, v247, 13
	s_lshl_b64 s[54:55], s[48:49], 11
	s_add_u32 s50, s50, s54
	s_addc_u32 s51, s51, s55
	global_load_dword v196, v194, s[68:69]
	global_load_dword v197, v194, s[68:69] offset:1024
	global_load_dword v198, v194, s[68:69] offset:2048
	global_load_dword v199, v195, s[50:51]
	global_load_dword v200, v194, s[50:51] offset:1024
	global_load_ushort v201, v192, s[74:75] offset:-1024
	global_load_ushort v202, v192, s[74:75] offset:-512
	global_load_ushort v203, v192, s[74:75]
	global_load_ushort v204, v192, s[70:71]
	global_load_ushort v205, v193, s[24:25]
	global_load_ushort v206, v193, s[24:25] offset:1536
	s_lshl_b64 s[2:3], s[48:49], 18
	v_readlane_b32 s64, v247, 14
	v_readlane_b32 s65, v247, 15
	v_ashrrev_i32_e32 v146, 5, v144
	v_lshlrev_b32_e32 v2, 2, v144
	s_add_u32 s46, s64, s2
	v_and_b32_e32 v148, 0x7c, v2
	v_readlane_b32 s66, v247, 16
	s_addc_u32 s47, s65, s3
	v_lshl_add_u32 v2, v146, 3, s33
	v_or_b32_e32 v14, s45, v148
	v_readlane_b32 s67, v247, 17
	s_add_u32 s2, s66, s2
	v_ashrrev_i32_e32 v3, 31, v2
	v_lshlrev_b32_e32 v130, 2, v14
	s_addc_u32 s3, s67, s3
	v_lshlrev_b64 v[66:67], 10, v[2:3]
	v_readlane_b32 s60, v247, 10
	v_lshl_add_u64 v[22:23], s[46:47], 0, v[130:131]
	v_lshl_add_u64 v[24:25], s[2:3], 0, v[130:131]
	v_lshl_add_u64 v[10:11], v[66:67], 0, s[6:7]
	s_lshl_b32 s2, s48, 2
	v_readlane_b32 s61, v247, 11
	v_lshl_add_u64 v[2:3], v[22:23], 0, v[66:67]
	v_lshl_add_u64 v[12:13], v[22:23], 0, v[10:11]
	s_add_i32 s60, s2, 0x4000
	global_load_dwordx4 v[110:113], v[2:3], off nt
	global_load_dwordx4 v[98:101], v[12:13], off nt
	v_lshl_add_u64 v[2:3], v[24:25], 0, v[66:67]
	v_lshlrev_b32_e32 v130, 1, v14
	s_ashr_i32 s61, s60, 31
	global_load_dwordx4 v[6:9], v[2:3], off nt
	v_lshl_add_u64 v[2:3], v[66:67], 0, s[4:5]
	v_lshl_add_u64 v[132:133], s[72:73], 0, v[130:131]
	s_lshl_b64 s[46:47], s[60:61], 9
	v_lshl_add_u64 v[4:5], v[22:23], 0, v[2:3]
	v_lshl_add_u64 v[2:3], v[24:25], 0, v[2:3]
	v_lshl_add_u64 v[12:13], v[132:133], 0, s[46:47]
	global_load_dwordx4 v[106:109], v[4:5], off nt
	v_lshl_add_u64 v[10:11], v[24:25], 0, v[10:11]
	global_load_dwordx4 v[2:5], v[2:3], off nt
	s_nop 0
	global_load_dwordx2 v[134:135], v[12:13], off
	global_load_dwordx4 v[62:65], v[10:11], off nt
	v_lshl_add_u64 v[10:11], v[66:67], 0, s[8:9]
	v_lshl_add_u64 v[12:13], v[22:23], 0, v[10:11]
	global_load_dwordx4 v[126:129], v[12:13], off nt
	v_lshl_add_u64 v[10:11], v[24:25], 0, v[10:11]
	v_lshl_add_u64 v[18:19], v[66:67], 0, s[38:39]
	global_load_dwordx4 v[50:53], v[10:11], off nt
	v_lshl_add_u64 v[10:11], v[66:67], 0, s[10:11]
	v_lshl_add_u64 v[20:21], v[22:23], 0, v[18:19]
	global_load_dwordx4 v[70:73], v[20:21], off nt
	v_lshl_add_u64 v[12:13], v[22:23], 0, v[10:11]
	global_load_dwordx4 v[122:125], v[12:13], off nt
	v_lshl_add_u64 v[10:11], v[24:25], 0, v[10:11]
	global_load_dwordx4 v[58:61], v[10:11], off nt
	v_lshl_add_u64 v[10:11], v[66:67], 0, s[12:13]
	v_lshl_add_u64 v[12:13], v[22:23], 0, v[10:11]
	global_load_dwordx4 v[118:121], v[12:13], off nt
	v_lshl_add_u64 v[10:11], v[24:25], 0, v[10:11]
	global_load_dwordx4 v[42:45], v[10:11], off nt
	v_lshl_add_u64 v[10:11], v[66:67], 0, s[14:15]
	v_lshl_add_u64 v[12:13], v[22:23], 0, v[10:11]
	global_load_dwordx4 v[114:117], v[12:13], off nt
	s_ashr_i32 s3, s2, 31
	s_lshl_b64 s[2:3], s[2:3], 9
	v_lshl_add_u64 v[10:11], v[24:25], 0, v[10:11]
	v_lshl_add_u64 v[132:133], v[132:133], 0, s[2:3]
	global_load_dwordx4 v[54:57], v[10:11], off nt
	v_lshl_add_u64 v[10:11], v[66:67], 0, s[16:17]
	v_add_co_u32_e32 v132, vcc, s40, v132
	v_lshl_add_u64 v[12:13], v[22:23], 0, v[10:11]
	s_nop 0
	v_addc_co_u32_e32 v133, vcc, 0, v133, vcc
	global_load_dwordx4 v[102:105], v[12:13], off nt
	v_cmp_lt_i32_e32 vcc, v147, v149
	v_lshl_add_u64 v[10:11], v[24:25], 0, v[10:11]
	global_load_dwordx4 v[34:37], v[10:11], off nt
	v_cndmask_b32_e32 v130, v1, v147, vcc
	v_lshlrev_b32_e32 v163, 2, v130
	v_cmp_lt_i32_e32 vcc, v151, v149
	v_lshl_add_u64 v[10:11], v[66:67], 0, s[18:19]
	v_lshl_add_u64 v[12:13], v[22:23], 0, v[10:11]
	v_cndmask_b32_e32 v130, v1, v151, vcc
	v_lshlrev_b32_e32 v168, 2, v130
	global_load_dwordx4 v[94:97], v[12:13], off nt
	v_lshl_add_u64 v[10:11], v[24:25], 0, v[10:11]
	global_load_dwordx4 v[46:49], v[10:11], off nt
	v_lshl_add_u64 v[10:11], v[66:67], 0, s[20:21]
	v_lshl_add_u64 v[12:13], v[22:23], 0, v[10:11]
	global_load_dwordx4 v[90:93], v[12:13], off nt
	v_cmp_lt_i32_e32 vcc, v153, v149
	v_lshl_add_u32 v161, v148, 2, 0
	v_lshl_add_u64 v[10:11], v[24:25], 0, v[10:11]
	v_cndmask_b32_e32 v130, v1, v153, vcc
	v_lshlrev_b32_e32 v167, 2, v130
	v_cmp_lt_i32_e32 vcc, v155, v149
	global_load_dwordx4 v[26:29], v[10:11], off nt
	v_lshl_add_u64 v[10:11], v[66:67], 0, s[22:23]
	v_cndmask_b32_e32 v130, v1, v155, vcc
	v_lshlrev_b32_e32 v165, 2, v130
	v_lshl_add_u64 v[12:13], v[22:23], 0, v[10:11]
	global_load_dwordx4 v[86:89], v[12:13], off nt
	v_lshl_add_u64 v[10:11], v[24:25], 0, v[10:11]
	global_load_dwordx4 v[38:41], v[10:11], off nt
	v_lshl_add_u64 v[10:11], v[66:67], 0, s[26:27]
	v_lshl_add_u64 v[12:13], v[22:23], 0, v[10:11]
	global_load_dwordx4 v[82:85], v[12:13], off nt
	v_lshl_add_u64 v[10:11], v[24:25], 0, v[10:11]
	global_load_dwordx4 v[14:17], v[10:11], off nt
	v_lshl_add_u64 v[10:11], v[66:67], 0, s[28:29]
	v_lshl_add_u64 v[12:13], v[22:23], 0, v[10:11]
	global_load_dwordx4 v[78:81], v[12:13], off nt
	v_lshl_add_u32 v159, v146, 2, s30
	v_lshl_add_u64 v[10:11], v[24:25], 0, v[10:11]
	global_load_dwordx4 v[30:33], v[10:11], off nt
	v_lshl_add_u64 v[10:11], v[66:67], 0, s[34:35]
	v_lshl_add_u64 v[12:13], v[22:23], 0, v[10:11]
	global_load_dwordx4 v[74:77], v[12:13], off nt
	v_lshl_add_u64 v[136:137], v[66:67], 0, s[42:43]
	s_waitcnt vmcnt(23)
; DI void unit_sample_mem(int u, const bf16* __restrict__ MQ, const float* __restrict__ cmk, const float* __restrict__ cmv, const bf16* __restrict__ G, bf16* __restrict__ MIX, const bf16* __restrict__ CB, const bf16* __restrict__ U, const float* __restrict__ cconv, const float* __restrict__ convw, ...
;     ...
;     for (int jj = 0; jj < 4; ++jj) { float s[16]; float mn = NEG;
; #pragma unroll
;         for (int i = 0; i < 16; ++i) { float d = (q[jj][0] * kv[i][0] + q[jj][1] * kv[i][1]) + (q[jj][2] * kv[i][2] + q[jj][3] * kv[i][3]);
;             d += __shfl_xor(d, 1); d += __shfl_xor(d, 2); d += __shfl_xor(d, 4); d += __shfl_xor(d, 8); s[i] = d; mn = fmaxf(mn, d); }
	v_and_b32_e32 v140, 0xffff0000, v134
	v_lshlrev_b32_e32 v142, 16, v134
	v_and_b32_e32 v143, 0xffff0000, v135
	v_mov_b32_e32 v134, v111
	v_mov_b32_e32 v111, v113
	v_lshlrev_b32_e32 v141, 16, v135
	v_mov_b32_e32 v135, v112
	v_pk_mul_f32 v[112:113], v[110:111], v[142:143]
	v_lshl_add_u64 v[22:23], v[22:23], 0, v[136:137]
	v_pk_fma_f32 v[112:113], v[134:135], v[140:141], v[112:113]
	global_load_dwordx4 v[66:69], v[22:23], off nt
	v_add_f32_e32 v112, v112, v113
	v_lshl_add_u64 v[10:11], v[24:25], 0, v[10:11]
	global_load_dwordx4 v[10:13], v[10:11], off nt
	v_lshl_add_u64 v[18:19], v[24:25], 0, v[18:19]
	global_load_dwordx4 v[18:21], v[18:19], off nt
	s_waitcnt lgkmcnt(0)
	v_add_f32_dpp v112, v112, v112 quad_perm:[1,0,3,2] row_mask:0xf bank_mask:0xf
	v_lshl_add_u64 v[22:23], v[24:25], 0, v[136:137]
	global_load_dwordx4 v[22:25], v[22:23], off nt
	s_nop 0
	global_load_dwordx2 v[138:139], v[132:133], off offset:512
	global_load_dwordx2 v[136:137], v[132:133], off offset:1024
	s_nop 0
	global_load_dwordx2 v[132:133], v[132:133], off offset:1536
	v_bfe_u32 v169, v144, 4, 1
	s_waitcnt lgkmcnt(0)
	v_add_f32_dpp v112, v112, v112 quad_perm:[2,3,0,1] row_mask:0xf bank_mask:0xf
	v_and_b32_e32 v144, 15, v144
	v_cmp_eq_u32_e32 vcc, 0, v144
	v_readlane_b32 s53, v247, 3
	v_readlane_b32 s54, v247, 4
	s_waitcnt lgkmcnt(0)
	v_add_f32_dpp v130, v112, v112 row_half_mirror row_mask:0xf bank_mask:0xf
	v_mov_b32_e32 v112, v107
	v_mov_b32_e32 v107, v109
	v_mov_b32_e32 v113, v108
	v_pk_mul_f32 v[108:109], v[106:107], v[142:143]
	v_pk_fma_f32 v[108:109], v[112:113], v[140:141], v[108:109]
	v_readlane_b32 s55, v247, 5
	v_add_f32_e32 v148, v108, v109
	v_mov_b32_e32 v108, v99
	v_mov_b32_e32 v99, v101
	v_mov_b32_e32 v109, v100
	v_pk_mul_f32 v[100:101], v[98:99], v[142:143]
	v_pk_fma_f32 v[100:101], v[108:109], v[140:141], v[100:101]
	s_waitcnt lgkmcnt(0)
	v_add_f32_dpp v130, v130, v130 row_mirror row_mask:0xf bank_mask:0xf
	v_add_f32_e32 v152, v100, v101
	s_waitcnt vmcnt(28)
	v_mov_b32_e32 v100, v127
	v_mov_b32_e32 v127, v129
	v_mov_b32_e32 v101, v128
	v_pk_mul_f32 v[128:129], v[126:127], v[142:143]
	v_pk_fma_f32 v[128:129], v[100:101], v[140:141], v[128:129]
	s_waitcnt lgkmcnt(0)
	v_add_f32_dpp v148, v148, v148 quad_perm:[1,0,3,2] row_mask:0xf bank_mask:0xf
	v_add_f32_e32 v128, v128, v129
	s_waitcnt lgkmcnt(0)
	v_add_f32_dpp v152, v152, v152 quad_perm:[1,0,3,2] row_mask:0xf bank_mask:0xf
	v_readlane_b32 s56, v247, 6
	s_waitcnt lgkmcnt(0)
	v_add_f32_dpp v128, v128, v128 quad_perm:[1,0,3,2] row_mask:0xf bank_mask:0xf
	s_waitcnt lgkmcnt(0)
	v_add_f32_dpp v148, v148, v148 quad_perm:[2,3,0,1] row_mask:0xf bank_mask:0xf
	s_waitcnt lgkmcnt(0)
	v_add_f32_dpp v152, v152, v152 quad_perm:[2,3,0,1] row_mask:0xf bank_mask:0xf
	s_waitcnt lgkmcnt(0)
	v_add_f32_dpp v128, v128, v128 quad_perm:[2,3,0,1] row_mask:0xf bank_mask:0xf
	v_readlane_b32 s57, v247, 7
	s_waitcnt lgkmcnt(0)
	v_add_f32_dpp v148, v148, v148 row_half_mirror row_mask:0xf bank_mask:0xf
	s_waitcnt lgkmcnt(0)
	v_add_f32_dpp v152, v152, v152 row_half_mirror row_mask:0xf bank_mask:0xf
	s_waitcnt lgkmcnt(0)
	v_add_f32_dpp v128, v128, v128 row_half_mirror row_mask:0xf bank_mask:0xf
	v_readlane_b32 s58, v247, 8
	s_waitcnt lgkmcnt(0)
	v_add_f32_dpp v146, v148, v148 row_mirror row_mask:0xf bank_mask:0xf
	v_max3_f32 v148, v130, s41, v146
	s_waitcnt lgkmcnt(0)
	v_add_f32_dpp v150, v152, v152 row_mirror row_mask:0xf bank_mask:0xf
	s_waitcnt lgkmcnt(0)
	v_add_f32_dpp v152, v128, v128 row_mirror row_mask:0xf bank_mask:0xf
	s_waitcnt vmcnt(25)
	v_mov_b32_e32 v128, v123
	v_mov_b32_e32 v123, v125
	v_mov_b32_e32 v129, v124
	v_pk_mul_f32 v[124:125], v[122:123], v[142:143]
	v_max3_f32 v148, v148, v150, v152
	v_pk_fma_f32 v[124:125], v[128:129], v[140:141], v[124:125]
	v_readlane_b32 s59, v247, 9
	v_add_f32_e32 v154, v124, v125
	s_waitcnt vmcnt(23)
	v_mov_b32_e32 v124, v119
	v_mov_b32_e32 v119, v121
	v_mov_b32_e32 v125, v120
	v_pk_mul_f32 v[120:121], v[118:119], v[142:143]
	v_pk_fma_f32 v[120:121], v[124:125], v[140:141], v[120:121]
	v_readlane_b32 s62, v247, 12
	v_add_f32_e32 v158, v120, v121
	s_waitcnt vmcnt(21)
	v_mov_b32_e32 v120, v115
	v_mov_b32_e32 v115, v117
	v_mov_b32_e32 v121, v116
	v_pk_mul_f32 v[116:117], v[114:115], v[142:143]
	v_pk_fma_f32 v[116:117], v[120:121], v[140:141], v[116:117]
	s_waitcnt lgkmcnt(0)
	v_add_f32_dpp v154, v154, v154 quad_perm:[1,0,3,2] row_mask:0xf bank_mask:0xf
	v_add_f32_e32 v116, v116, v117
	s_waitcnt lgkmcnt(0)
	v_add_f32_dpp v158, v158, v158 quad_perm:[1,0,3,2] row_mask:0xf bank_mask:0xf
	v_readlane_b32 s63, v247, 13
	s_waitcnt lgkmcnt(0)
	v_add_f32_dpp v116, v116, v116 quad_perm:[1,0,3,2] row_mask:0xf bank_mask:0xf
	s_waitcnt lgkmcnt(0)
	v_add_f32_dpp v154, v154, v154 quad_perm:[2,3,0,1] row_mask:0xf bank_mask:0xf
	s_waitcnt lgkmcnt(0)
	v_add_f32_dpp v158, v158, v158 quad_perm:[2,3,0,1] row_mask:0xf bank_mask:0xf
	s_waitcnt lgkmcnt(0)
	v_add_f32_dpp v116, v116, v116 quad_perm:[2,3,0,1] row_mask:0xf bank_mask:0xf
	s_waitcnt lgkmcnt(0)
	v_add_f32_dpp v154, v154, v154 row_half_mirror row_mask:0xf bank_mask:0xf
	s_waitcnt lgkmcnt(0)
	v_add_f32_dpp v158, v158, v158 row_half_mirror row_mask:0xf bank_mask:0xf
	s_waitcnt lgkmcnt(0)
	v_add_f32_dpp v162, v116, v116 row_half_mirror row_mask:0xf bank_mask:0xf
	s_waitcnt vmcnt(19)
	v_mov_b32_e32 v116, v103
	v_mov_b32_e32 v103, v105
	v_mov_b32_e32 v117, v104
	v_pk_mul_f32 v[104:105], v[102:103], v[142:143]
	v_pk_fma_f32 v[104:105], v[116:117], v[140:141], v[104:105]
	v_add_f32_e32 v104, v104, v105
	s_waitcnt lgkmcnt(0)
	v_add_f32_dpp v154, v154, v154 row_mirror row_mask:0xf bank_mask:0xf
	s_waitcnt lgkmcnt(0)
	v_add_f32_dpp v156, v158, v158 row_mirror row_mask:0xf bank_mask:0xf
	s_waitcnt lgkmcnt(0)
; DI void unit_sample_mem(int u, const bf16* __restrict__ MQ, const float* __restrict__ cmk, const float* __restrict__ cmv, const bf16* __restrict__ G, bf16* __restrict__ MIX, const bf16* __restrict__ CB, const bf16* __restrict__ U, const float* __restrict__ cconv, const float* __restrict__ convw, ...
;     ...
; #pragma unroll
;         for (int i = 0; i < 16; ++i) { float d = (q[jj][0] * kv[i][0] + q[jj][1] * kv[i][1]) + (q[jj][2] * kv[i][2] + q[jj][3] * kv[i][3]);
;             d += __shfl_xor(d, 1); d += __shfl_xor(d, 2); d += __shfl_xor(d, 4); d += __shfl_xor(d, 8); s[i] = d; mn = fmaxf(mn, d); }
	v_add_f32_dpp v158, v162, v162 row_mirror row_mask:0xf bank_mask:0xf
	v_max3_f32 v148, v148, v154, v156
	s_waitcnt lgkmcnt(0)
	v_add_f32_dpp v160, v104, v104 quad_perm:[1,0,3,2] row_mask:0xf bank_mask:0xf
	s_waitcnt vmcnt(17)
	v_mov_b32_e32 v104, v95
	v_mov_b32_e32 v95, v97
	v_mov_b32_e32 v105, v96
	v_pk_mul_f32 v[96:97], v[94:95], v[142:143]
	v_pk_fma_f32 v[96:97], v[104:105], v[140:141], v[96:97]
	s_waitcnt lgkmcnt(0)
	v_add_f32_dpp v160, v160, v160 quad_perm:[2,3,0,1] row_mask:0xf bank_mask:0xf
	v_add_f32_e32 v164, v96, v97
	s_waitcnt vmcnt(15)
	v_mov_b32_e32 v96, v91
	v_mov_b32_e32 v91, v93
	v_mov_b32_e32 v97, v92
	v_pk_mul_f32 v[92:93], v[90:91], v[142:143]
	v_pk_fma_f32 v[92:93], v[96:97], v[140:141], v[92:93]
	v_add_f32_e32 v92, v92, v93
	s_waitcnt lgkmcnt(0)
	v_add_f32_dpp v164, v164, v164 quad_perm:[1,0,3,2] row_mask:0xf bank_mask:0xf
	s_waitcnt lgkmcnt(0)
	v_add_f32_dpp v160, v160, v160 row_half_mirror row_mask:0xf bank_mask:0xf
	s_waitcnt lgkmcnt(0)
	v_add_f32_dpp v92, v92, v92 quad_perm:[1,0,3,2] row_mask:0xf bank_mask:0xf
	s_waitcnt lgkmcnt(0)
	v_add_f32_dpp v164, v164, v164 quad_perm:[2,3,0,1] row_mask:0xf bank_mask:0xf
	s_waitcnt lgkmcnt(0)
	v_add_f32_dpp v160, v160, v160 row_mirror row_mask:0xf bank_mask:0xf
	v_max3_f32 v148, v148, v158, v160
	s_waitcnt lgkmcnt(0)
	v_add_f32_dpp v92, v92, v92 quad_perm:[2,3,0,1] row_mask:0xf bank_mask:0xf
	s_waitcnt lgkmcnt(0)
	v_add_f32_dpp v162, v164, v164 row_half_mirror row_mask:0xf bank_mask:0xf
	s_waitcnt lgkmcnt(0)
	v_add_f32_dpp v166, v92, v92 row_half_mirror row_mask:0xf bank_mask:0xf
	s_waitcnt vmcnt(13)
	v_mov_b32_e32 v92, v87
	v_mov_b32_e32 v87, v89
	v_mov_b32_e32 v93, v88
	v_pk_mul_f32 v[88:89], v[86:87], v[142:143]
	v_pk_fma_f32 v[88:89], v[92:93], v[140:141], v[88:89]
	s_waitcnt lgkmcnt(0)
	v_add_f32_dpp v162, v162, v162 row_mirror row_mask:0xf bank_mask:0xf
	v_add_f32_e32 v171, v88, v89
	s_waitcnt vmcnt(11)
	v_mov_b32_e32 v88, v83
	v_mov_b32_e32 v83, v85
	v_mov_b32_e32 v89, v84
	v_pk_mul_f32 v[84:85], v[82:83], v[142:143]
	v_pk_fma_f32 v[84:85], v[88:89], v[140:141], v[84:85]
	s_waitcnt lgkmcnt(0)
	v_add_f32_dpp v164, v166, v166 row_mirror row_mask:0xf bank_mask:0xf
	v_add_f32_e32 v84, v84, v85
	s_waitcnt lgkmcnt(0)
	v_add_f32_dpp v166, v171, v171 quad_perm:[1,0,3,2] row_mask:0xf bank_mask:0xf
	v_max3_f32 v148, v148, v162, v164
	s_waitcnt lgkmcnt(0)
	v_add_f32_dpp v171, v84, v84 quad_perm:[1,0,3,2] row_mask:0xf bank_mask:0xf
	s_waitcnt vmcnt(9)
	v_mov_b32_e32 v84, v79
	v_mov_b32_e32 v79, v81
	v_mov_b32_e32 v85, v80
	v_pk_mul_f32 v[80:81], v[78:79], v[142:143]
	v_pk_fma_f32 v[80:81], v[84:85], v[140:141], v[80:81]
	s_waitcnt lgkmcnt(0)
	v_add_f32_dpp v166, v166, v166 quad_perm:[2,3,0,1] row_mask:0xf bank_mask:0xf
	v_add_f32_e32 v80, v80, v81
	s_waitcnt lgkmcnt(0)
	v_add_f32_dpp v171, v171, v171 quad_perm:[2,3,0,1] row_mask:0xf bank_mask:0xf
	s_waitcnt lgkmcnt(0)
	v_add_f32_dpp v80, v80, v80 quad_perm:[1,0,3,2] row_mask:0xf bank_mask:0xf
	s_waitcnt lgkmcnt(0)
	v_add_f32_dpp v166, v166, v166 row_half_mirror row_mask:0xf bank_mask:0xf
	s_waitcnt lgkmcnt(0)
	v_add_f32_dpp v171, v171, v171 row_half_mirror row_mask:0xf bank_mask:0xf
	s_waitcnt lgkmcnt(0)
	v_add_f32_dpp v80, v80, v80 quad_perm:[2,3,0,1] row_mask:0xf bank_mask:0xf
	s_waitcnt lgkmcnt(0)
	v_add_f32_dpp v166, v166, v166 row_mirror row_mask:0xf bank_mask:0xf
	s_waitcnt lgkmcnt(0)
	v_add_f32_dpp v174, v171, v171 row_mirror row_mask:0xf bank_mask:0xf
	v_max3_f32 v148, v148, v166, v174
	s_waitcnt lgkmcnt(0)
	v_add_f32_dpp v170, v80, v80 row_half_mirror row_mask:0xf bank_mask:0xf
	s_waitcnt vmcnt(7)
	v_mov_b32_e32 v80, v75
	v_mov_b32_e32 v75, v77
	v_mov_b32_e32 v81, v76
	v_pk_mul_f32 v[76:77], v[74:75], v[142:143]
	v_pk_fma_f32 v[76:77], v[80:81], v[140:141], v[76:77]
	s_nop 0
	v_add_f32_e32 v172, v76, v77
	v_mov_b32_e32 v76, v71
	v_mov_b32_e32 v71, v73
	v_mov_b32_e32 v77, v72
	v_pk_mul_f32 v[72:73], v[70:71], v[142:143]
	v_pk_fma_f32 v[72:73], v[76:77], v[140:141], v[72:73]
	s_nop 0
	v_add_f32_e32 v175, v72, v73
	s_waitcnt vmcnt(6)
	v_mov_b32_e32 v72, v67
	v_mov_b32_e32 v67, v69
	v_mov_b32_e32 v73, v68
	v_pk_mul_f32 v[68:69], v[66:67], v[142:143]
	v_pk_fma_f32 v[68:69], v[72:73], v[140:141], v[68:69]
	s_waitcnt lgkmcnt(0)
	v_add_f32_dpp v140, v172, v172 quad_perm:[1,0,3,2] row_mask:0xf bank_mask:0xf
	v_add_f32_e32 v68, v68, v69
	s_waitcnt lgkmcnt(0)
	v_add_f32_dpp v142, v175, v175 quad_perm:[1,0,3,2] row_mask:0xf bank_mask:0xf
	v_add_f32_dpp v175, v170, v170 row_mirror row_mask:0xf bank_mask:0xf
	s_waitcnt lgkmcnt(0)
	v_add_f32_dpp v68, v68, v68 quad_perm:[1,0,3,2] row_mask:0xf bank_mask:0xf
	s_waitcnt lgkmcnt(0)
	v_add_f32_dpp v140, v140, v140 quad_perm:[2,3,0,1] row_mask:0xf bank_mask:0xf
	s_waitcnt lgkmcnt(0)
	v_add_f32_dpp v142, v142, v142 quad_perm:[2,3,0,1] row_mask:0xf bank_mask:0xf
	s_waitcnt lgkmcnt(0)
; #define LAS __attribute__((address_space(3)))
; DI float fexp2(float x) { return __builtin_amdgcn_exp2f(x); }
; DI void unit_sample_mem(int u, const bf16* __restrict__ MQ, const float* __restrict__ cmk, const float* __restrict__ cmv, const bf16* __restrict__ G, bf16* __restrict__ MIX, const bf16* __restrict__ CB, const bf16* __restrict__ U, const float* __restrict__ cconv, const float* __restrict__ convw, ...
;     ...
;         float ps = 0.f; f32x4 acc = (f32x4){0.f, 0.f, 0.f, 0.f};
; #pragma unroll
;         for (int i = 0; i < 16; ++i) { const float p = fexp2(s[i] - mn); ps += p; acc += vv[i] * p; }
;         *(LAS f32x4*)(so + (pst * 4 + jj) * 128 + l32 * 4) = acc;
;         if ((lane & 15) == 0) { sm[(pst * 4 + jj) * 2 + hd] = mn; sl[(pst * 4 + jj) * 2 + hd] = ps; } }
	v_add_f32_dpp v68, v68, v68 quad_perm:[2,3,0,1] row_mask:0xf bank_mask:0xf
	s_waitcnt lgkmcnt(0)
	v_add_f32_dpp v140, v140, v140 row_half_mirror row_mask:0xf bank_mask:0xf
	s_waitcnt lgkmcnt(0)
	v_add_f32_dpp v142, v142, v142 row_half_mirror row_mask:0xf bank_mask:0xf
	s_waitcnt lgkmcnt(0)
	v_add_f32_dpp v68, v68, v68 row_half_mirror row_mask:0xf bank_mask:0xf
	s_waitcnt lgkmcnt(0)
	v_add_f32_dpp v176, v140, v140 row_mirror row_mask:0xf bank_mask:0xf
	v_max3_f32 v140, v148, v175, v176
	s_waitcnt lgkmcnt(0)
	v_add_f32_dpp v177, v142, v142 row_mirror row_mask:0xf bank_mask:0xf
	s_waitcnt lgkmcnt(0)
	v_add_f32_dpp v69, v68, v68 row_mirror row_mask:0xf bank_mask:0xf
	v_max3_f32 v141, v140, v177, v69
	v_sub_f32_e32 v68, v130, v141
	v_exp_f32_e32 v68, v68
	v_sub_f32_e32 v130, v146, v141
	v_exp_f32_e32 v130, v130
	v_sub_f32_e32 v140, v150, v141
	v_pk_fma_f32 v[142:143], v[8:9], v[68:69], 0 op_sel_hi:[1,0,0]
	v_exp_f32_e32 v140, v140
	v_pk_fma_f32 v[172:173], v[4:5], v[130:131], v[142:143] op_sel_hi:[1,0,1]
	v_sub_f32_e32 v142, v152, v141
	v_exp_f32_e32 v142, v142
	v_pk_fma_f32 v[170:171], v[6:7], v[68:69], 0 op_sel_hi:[1,0,0]
	v_pk_fma_f32 v[172:173], v[64:65], v[140:141], v[172:173] op_sel_hi:[1,0,1]
	v_pk_fma_f32 v[170:171], v[2:3], v[130:131], v[170:171] op_sel_hi:[1,0,1]
	v_pk_fma_f32 v[172:173], v[52:53], v[142:143], v[172:173] op_sel_hi:[1,0,1]
	v_sub_f32_e32 v143, v154, v141
	v_pk_fma_f32 v[170:171], v[62:63], v[140:141], v[170:171] op_sel_hi:[1,0,1]
	v_exp_f32_e32 v144, v143
	v_sub_f32_e32 v143, v156, v141
	v_exp_f32_e32 v146, v143
	v_pk_fma_f32 v[170:171], v[50:51], v[142:143], v[170:171] op_sel_hi:[1,0,1]
	v_sub_f32_e32 v143, v158, v141
	v_exp_f32_e32 v148, v143
	v_sub_f32_e32 v143, v160, v141
	v_exp_f32_e32 v150, v143
	v_sub_f32_e32 v143, v162, v141
	v_pk_fma_f32 v[170:171], v[58:59], v[144:145], v[170:171] op_sel_hi:[1,0,1]
	v_pk_fma_f32 v[172:173], v[60:61], v[144:145], v[172:173] op_sel_hi:[1,0,1]
	v_exp_f32_e32 v152, v143
	v_sub_f32_e32 v143, v164, v141
	v_pk_fma_f32 v[172:173], v[44:45], v[146:147], v[172:173] op_sel_hi:[1,0,1]
	v_pk_fma_f32 v[170:171], v[42:43], v[146:147], v[170:171] op_sel_hi:[1,0,1]
	v_exp_f32_e32 v154, v143
	v_sub_f32_e32 v143, v166, v141
	v_pk_fma_f32 v[170:171], v[54:55], v[148:149], v[170:171] op_sel_hi:[1,0,1]
	v_pk_fma_f32 v[172:173], v[56:57], v[148:149], v[172:173] op_sel_hi:[1,0,1]
	v_exp_f32_e32 v156, v143
	v_sub_f32_e32 v143, v174, v141
	v_pk_fma_f32 v[172:173], v[36:37], v[150:151], v[172:173] op_sel_hi:[1,0,1]
	v_pk_fma_f32 v[170:171], v[34:35], v[150:151], v[170:171] op_sel_hi:[1,0,1]
	v_exp_f32_e32 v158, v143
	v_sub_f32_e32 v143, v175, v141
	v_pk_fma_f32 v[170:171], v[46:47], v[152:153], v[170:171] op_sel_hi:[1,0,1]
	v_pk_fma_f32 v[172:173], v[48:49], v[152:153], v[172:173] op_sel_hi:[1,0,1]
	v_exp_f32_e32 v160, v143
	v_sub_f32_e32 v143, v176, v141
	v_pk_fma_f32 v[172:173], v[28:29], v[154:155], v[172:173] op_sel_hi:[1,0,1]
	v_pk_fma_f32 v[170:171], v[26:27], v[154:155], v[170:171] op_sel_hi:[1,0,1]
	v_exp_f32_e32 v162, v143
	v_sub_f32_e32 v143, v177, v141
	v_pk_fma_f32 v[170:171], v[38:39], v[156:157], v[170:171] op_sel_hi:[1,0,1]
	v_pk_fma_f32 v[172:173], v[40:41], v[156:157], v[172:173] op_sel_hi:[1,0,1]
	v_exp_f32_e32 v164, v143
	v_sub_f32_e32 v69, v69, v141
	v_pk_fma_f32 v[172:173], v[16:17], v[158:159], v[172:173] op_sel_hi:[1,0,1]
	v_pk_fma_f32 v[170:171], v[14:15], v[158:159], v[170:171] op_sel_hi:[1,0,1]
	v_exp_f32_e32 v166, v69
	v_pk_fma_f32 v[170:171], v[30:31], v[160:161], v[170:171] op_sel_hi:[1,0,1]
	v_pk_fma_f32 v[172:173], v[32:33], v[160:161], v[172:173] op_sel_hi:[1,0,1]
	s_waitcnt vmcnt(5)
	v_pk_fma_f32 v[170:171], v[10:11], v[162:163], v[170:171] op_sel_hi:[1,0,1]
	v_pk_fma_f32 v[172:173], v[12:13], v[162:163], v[172:173] op_sel_hi:[1,0,1]
	s_waitcnt vmcnt(4)
	v_pk_fma_f32 v[170:171], v[18:19], v[164:165], v[170:171] op_sel_hi:[1,0,1]
	v_pk_fma_f32 v[172:173], v[20:21], v[164:165], v[172:173] op_sel_hi:[1,0,1]
	s_waitcnt vmcnt(3)
	v_pk_fma_f32 v[170:171], v[22:23], v[166:167], v[170:171] op_sel_hi:[1,0,1]
	v_pk_fma_f32 v[172:173], v[24:25], v[166:167], v[172:173] op_sel_hi:[1,0,1]
	v_lshl_add_u32 v69, v159, 9, v161
	ds_write_b128 v69, v[170:173]
	v_lshlrev_b32_e32 v69, 2, v169
	s_and_saveexec_b64 s[2:3], vcc
	s_cbranch_execz .LBB0_838
	v_add_f32_e32 v68, 0, v68
	v_add_f32_e32 v68, v130, v68
	v_add_f32_e32 v68, v140, v68
	v_add_f32_e32 v68, v142, v68
	v_add_f32_e32 v68, v144, v68
	v_add_f32_e32 v68, v146, v68
	v_add_f32_e32 v68, v148, v68
	v_add_f32_e32 v68, v150, v68
	v_add_f32_e32 v68, v152, v68
	v_add_f32_e32 v68, v154, v68
	v_add_f32_e32 v68, v156, v68
	v_add_f32_e32 v68, v158, v68
	v_add_f32_e32 v68, v160, v68
	v_add_f32_e32 v68, v162, v68
	v_add_f32_e32 v68, v164, v68
	v_lshl_or_b32 v130, v159, 3, v69
	v_add_f32_e32 v68, v166, v68
	v_add_u32_e32 v130, 0, v130
	ds_write2st64_b32 v130, v141, v68 offset0:128 offset1:130

; DI float fexp2(float x) { return __builtin_amdgcn_exp2f(x); }
; DI void unit_sample_mem(int u, const bf16* __restrict__ MQ, const float* __restrict__ cmk, const float* __restrict__ cmv, const bf16* __restrict__ G, bf16* __restrict__ MIX, const bf16* __restrict__ CB, const bf16* __restrict__ U, const float* __restrict__ cconv, const float* __restrict__ convw, ...
;     ...
;     {   const int jj = tid >> 7, e = tid & 127, h2 = e >> 6; float M = NEG;
; #pragma unroll
;         for (int w = 0; w < 16; ++w) M = fmaxf(M, sm[(w * 4 + jj) * 2 + h2]);
;         float num = 0.f, den = 0.f;
; #pragma unroll
;         for (int w = 0; w < 16; ++w) { const float f = fexp2(sm[(w * 4 + jj) * 2 + h2] - M); num += f * so[(w * 4 + jj) * 128 + e]; den += f * sl[(w * 4 + jj) * 2 + h2]; }
;         const size_t srow = (size_t)(MP + b * 4 + jj); const int col = 768 + hh * 128 + e;
;         const float g = bflo((unsigned)G[srow * D + col]);
.LBB0_844:
	s_or_b64 exec, exec, s[2:3]
	v_ashrrev_i32_e32 v2, 7, v157
	v_lshrrev_b32_e32 v4, 4, v157
	v_lshlrev_b32_e32 v14, 3, v2
	v_and_b32_e32 v15, 4, v4
	v_add3_u32 v4, 0, v14, v15
	v_add_u32_e32 v16, 0x8000, v4
	s_waitcnt lgkmcnt(0)
	s_barrier
	ds_read2_b32 v[4:5], v16 offset1:8
	ds_read2_b32 v[6:7], v16 offset0:16 offset1:24
	ds_read2_b32 v[8:9], v16 offset0:32 offset1:40
	ds_read2_b32 v[10:11], v16 offset0:48 offset1:56
	ds_read2_b32 v[12:13], v16 offset0:64 offset1:72
	s_waitcnt lgkmcnt(4)
	v_max3_f32 v4, v4, s41, v5
	s_waitcnt lgkmcnt(3)
	v_max3_f32 v4, v4, v6, v7
	s_waitcnt lgkmcnt(2)
	v_max3_f32 v4, v4, v8, v9
	s_waitcnt lgkmcnt(1)
	v_max3_f32 v4, v4, v10, v11
	v_or_b32_e32 v10, v14, v15
	s_waitcnt lgkmcnt(0)
	v_max3_f32 v12, v4, v12, v13
	ds_read2_b32 v[4:5], v16 offset0:80 offset1:88
	ds_read2_b32 v[6:7], v16 offset0:96 offset1:104
	ds_read2_b32 v[8:9], v16 offset0:112 offset1:120
	v_add_u32_e32 v10, 0, v10
	ds_read2st64_b32 v[10:11], v10 offset0:128 offset1:130
	s_waitcnt lgkmcnt(3)
	v_max3_f32 v4, v12, v4, v5
	s_waitcnt lgkmcnt(2)
	v_max3_f32 v4, v4, v6, v7
	s_waitcnt lgkmcnt(1)
	v_max3_f32 v13, v4, v8, v9
	v_add_u32_e32 v5, 4, v2
	s_waitcnt lgkmcnt(0)
	v_sub_f32_e32 v4, v10, v13
	v_lshl_or_b32 v6, v5, 3, v15
	v_add_u32_e32 v10, 8, v2
	v_add_u32_e32 v6, 0, v6
	v_lshl_or_b32 v8, v10, 3, v15
	ds_read2st64_b32 v[6:7], v6 offset0:128 offset1:130
	v_add_u32_e32 v8, 0, v8
	ds_read2st64_b32 v[8:9], v8 offset0:128 offset1:130
	v_and_b32_e32 v3, 0x7f, v157
	v_lshl_add_u32 v33, v3, 2, 0
	s_waitcnt lgkmcnt(1)
	v_sub_f32_e32 v6, v6, v13
	v_exp_f32_e32 v12, v6
	s_waitcnt lgkmcnt(0)
	v_sub_f32_e32 v6, v8, v13
	v_exp_f32_e32 v14, v6
	v_add_u32_e32 v6, 12, v2
	v_lshl_or_b32 v8, v6, 3, v15
	v_add_u32_e32 v8, 0, v8
	ds_read2st64_b32 v[16:17], v8 offset0:128 offset1:130
	v_add_u32_e32 v8, 16, v2
	v_lshl_or_b32 v18, v8, 3, v15
	v_add_u32_e32 v18, 0, v18
	ds_read2st64_b32 v[18:19], v18 offset0:128 offset1:130
	v_lshl_add_u32 v28, v10, 9, v33
	s_waitcnt lgkmcnt(1)
	v_sub_f32_e32 v10, v16, v13
	v_lshl_add_u32 v16, v6, 9, v33
	v_add_u32_e32 v6, 20, v2
	s_waitcnt lgkmcnt(0)
	v_sub_f32_e32 v29, v18, v13
	v_lshl_add_u32 v18, v8, 9, v33
	v_lshl_or_b32 v8, v6, 3, v15
	v_add_u32_e32 v8, 0, v8
	ds_read2st64_b32 v[22:23], v8 offset0:128 offset1:130
	v_add_u32_e32 v8, 24, v2
	v_exp_f32_e32 v20, v10
	v_lshl_or_b32 v10, v8, 3, v15
	v_add_u32_e32 v10, 0, v10
	ds_read2st64_b32 v[24:25], v10 offset0:128 offset1:130
	v_add_u32_e32 v10, 28, v2
	v_lshl_or_b32 v26, v10, 3, v15
	v_add_u32_e32 v26, 0, v26
	ds_read2st64_b32 v[26:27], v26 offset0:128 offset1:130
	v_exp_f32_e32 v4, v4
	v_lshl_add_u32 v21, v2, 9, v33
	v_lshl_add_u32 v5, v5, 9, v33
	s_waitcnt lgkmcnt(2)
	v_sub_f32_e32 v30, v22, v13
	v_lshl_add_u32 v22, v6, 9, v33
	s_waitcnt lgkmcnt(1)
	v_sub_f32_e32 v31, v24, v13
	v_lshl_add_u32 v24, v8, 9, v33
	s_waitcnt lgkmcnt(0)
	v_sub_f32_e32 v32, v26, v13
	v_lshl_add_u32 v26, v10, 9, v33
	ds_read_b32 v10, v21
	ds_read_b32 v6, v5
	ds_read_b32 v8, v28
	ds_read_b32 v16, v16
	ds_read_b32 v18, v18
	ds_read_b32 v22, v22
	ds_read_b32 v24, v24
	ds_read_b32 v26, v26
	s_waitcnt lgkmcnt(7)
	v_pk_fma_f32 v[4:5], v[10:11], v[4:5], 0 op_sel_hi:[1,0,0]
	v_exp_f32_e32 v32, v32
	s_waitcnt lgkmcnt(6)
	v_pk_fma_f32 v[4:5], v[6:7], v[12:13], v[4:5] op_sel_hi:[1,0,1]
	v_exp_f32_e32 v12, v29
	s_waitcnt lgkmcnt(5)
	v_pk_fma_f32 v[4:5], v[8:9], v[14:15], v[4:5] op_sel_hi:[1,0,1]
	v_add_u32_e32 v8, s60, v2
	s_waitcnt lgkmcnt(4)
	v_pk_fma_f32 v[10:11], v[16:17], v[20:21], v[4:5] op_sel_hi:[1,0,1]
	v_add_u32_e32 v5, 32, v2
	v_lshl_or_b32 v4, v5, 3, v15
	v_ashrrev_i32_e32 v9, 31, v8
	v_add_u32_e32 v17, 0, v4
	v_or_b32_e32 v4, s45, v3
	v_lshlrev_b64 v[6:7], 10, v[8:9]
	v_or3_b32 v20, v4, v6, s44
	v_mov_b32_e32 v21, v7
	v_lshlrev_b64 v[20:21], 1, v[20:21]
	ds_read2st64_b32 v[28:29], v17 offset0:128 offset1:130
	v_add_u32_e32 v17, 36, v2
	v_exp_f32_e32 v14, v30
	v_lshl_or_b32 v30, v17, 3, v15
	v_add_u32_e32 v30, 0, v30
	v_exp_f32_e32 v16, v31
	ds_read2st64_b32 v[30:31], v30 offset0:128 offset1:130
	s_waitcnt lgkmcnt(1)
	v_sub_f32_e32 v28, v28, v13
	v_exp_f32_e32 v34, v28
	v_lshl_add_u32 v17, v17, 9, v33
	v_lshl_add_u32 v5, v5, 9, v33
	s_waitcnt lgkmcnt(0)
; DI unsigned cvtpk(float lo, float hi) { f32x2_t v = {lo, hi}; bf16x2_t b = __builtin_convertvector(v, bf16x2_t); return __builtin_bit_cast(unsigned, b); }
; DI void unit_sample_mem(int u, const bf16* __restrict__ MQ, const float* __restrict__ cmk, const float* __restrict__ cmv, const bf16* __restrict__ G, bf16* __restrict__ MIX, const bf16* __restrict__ CB, const bf16* __restrict__ U, const float* __restrict__ cconv, const float* __restrict__ convw, ...
;     ...
;         const size_t srow = (size_t)(MP + b * 4 + jj); const int col = 768 + hh * 128 + e;
;         const float g = bflo((unsigned)G[srow * D + col]);
;         MIX[srow * D + col] = (bf16)(cvtpk(num / den * g, 0.f) & 0xffffu); }
;     {   const int jj = tid >> 7, c = hh * 128 + (tid & 127); const size_t srow = (size_t)(MP + b * 4 + jj);
;         const float f0 = (jj >= 2) ? bflo((unsigned)U[(srow - 2) * 256 + c]) : cconv[((size_t)b * 2 + jj) * 256 + c];
;         const float f1 = (jj >= 1) ? bflo((unsigned)U[(srow - 1) * 256 + c]) : cconv[((size_t)b * 2 + 1) * 256 + c];
;         const float f2 = bflo((unsigned)U[srow * 256 + c]);
;         const float val = bflo((unsigned)CB[srow * 256 + c]) * (convw[c] * f0 + convw[256 + c] * f1 + convw[512 + c] * f2) * bflo((unsigned)G[srow * D + c]);
;         MIX[srow * D + c] = (bf16)(cvtpk(val, 0.f) & 0xffffu); }
	v_sub_f32_e32 v28, v30, v13
	v_exp_f32_e32 v36, v28
	v_add_u32_e32 v28, 40, v2
	v_lshl_or_b32 v30, v28, 3, v15
	v_add_u32_e32 v30, 0, v30
	ds_read2st64_b32 v[38:39], v30 offset0:128 offset1:130
	v_add_u32_e32 v30, 44, v2
	v_lshl_or_b32 v35, v30, 3, v15
	v_add_u32_e32 v35, 0, v35
	ds_read2st64_b32 v[40:41], v35 offset0:128 offset1:130
	s_waitcnt lgkmcnt(1)
	v_sub_f32_e32 v35, v38, v13
	v_exp_f32_e32 v42, v35
	v_lshl_add_u32 v35, v28, 9, v33
	s_waitcnt lgkmcnt(0)
	v_sub_f32_e32 v28, v40, v13
	v_exp_f32_e32 v44, v28
	v_add_u32_e32 v28, 48, v2
	v_lshl_or_b32 v37, v28, 3, v15
	v_add_u32_e32 v37, 0, v37
	ds_read2st64_b32 v[46:47], v37 offset0:128 offset1:130
	v_add_u32_e32 v37, 52, v2
	v_lshl_or_b32 v38, v37, 3, v15
	v_add_u32_e32 v38, 0, v38
	ds_read2st64_b32 v[48:49], v38 offset0:128 offset1:130
	v_lshl_add_u32 v43, v28, 9, v33
	v_lshl_add_u32 v40, v30, 9, v33
	s_waitcnt lgkmcnt(1)
	v_sub_f32_e32 v30, v46, v13
	v_exp_f32_e32 v50, v30
	s_waitcnt lgkmcnt(0)
	v_sub_f32_e32 v28, v48, v13
	v_exp_f32_e32 v52, v28
	v_add_u32_e32 v28, 56, v2
	v_lshl_or_b32 v30, v28, 3, v15
	v_add_u32_e32 v30, 0, v30
	ds_read2st64_b32 v[54:55], v30 offset0:128 offset1:130
	v_add_u32_e32 v30, 60, v2
	v_lshl_or_b32 v15, v30, 3, v15
	v_add_u32_e32 v15, 0, v15
	ds_read2st64_b32 v[56:57], v15 offset0:128 offset1:130
	v_lshl_add_u32 v15, v37, 9, v33
	s_waitcnt lgkmcnt(1)
	v_sub_f32_e32 v37, v54, v13
	v_exp_f32_e32 v58, v37
	v_lshl_add_u32 v37, v28, 9, v33
	s_waitcnt lgkmcnt(0)
	v_sub_f32_e32 v13, v56, v13
	v_exp_f32_e32 v60, v13
	v_lshl_add_u32 v13, v30, 9, v33
	v_pk_fma_f32 v[10:11], v[18:19], v[12:13], v[10:11] op_sel_hi:[1,0,1]
	ds_read_b32 v28, v5
	ds_read_b32 v30, v17
	ds_read_b32 v38, v35
	ds_read_b32 v40, v40
	ds_read_b32 v46, v43
	ds_read_b32 v48, v15
	ds_read_b32 v54, v37
	ds_read_b32 v56, v13
	v_pk_fma_f32 v[10:11], v[22:23], v[14:15], v[10:11] op_sel_hi:[1,0,1]
	v_lshlrev_b32_e32 v3, 16, v206
	v_pk_fma_f32 v[10:11], v[24:25], v[16:17], v[10:11] op_sel_hi:[1,0,1]
	s_nop 0
	v_pk_fma_f32 v[10:11], v[26:27], v[32:33], v[10:11] op_sel_hi:[1,0,1]
	s_waitcnt lgkmcnt(7)
	v_pk_fma_f32 v[10:11], v[28:29], v[34:35], v[10:11] op_sel_hi:[1,0,1]
	s_waitcnt lgkmcnt(6)
	v_pk_fma_f32 v[10:11], v[30:31], v[36:37], v[10:11] op_sel_hi:[1,0,1]
	s_waitcnt lgkmcnt(5)
	v_pk_fma_f32 v[10:11], v[38:39], v[42:43], v[10:11] op_sel_hi:[1,0,1]
	s_waitcnt lgkmcnt(4)
	v_pk_fma_f32 v[10:11], v[40:41], v[44:45], v[10:11] op_sel_hi:[1,0,1]
	s_waitcnt lgkmcnt(3)
	v_pk_fma_f32 v[10:11], v[46:47], v[50:51], v[10:11] op_sel_hi:[1,0,1]
	s_waitcnt lgkmcnt(2)
	v_pk_fma_f32 v[10:11], v[48:49], v[52:53], v[10:11] op_sel_hi:[1,0,1]
	s_waitcnt lgkmcnt(1)
	v_pk_fma_f32 v[10:11], v[54:55], v[58:59], v[10:11] op_sel_hi:[1,0,1]
	s_waitcnt lgkmcnt(0)
	v_pk_fma_f32 v[10:11], v[56:57], v[60:61], v[10:11] op_sel_hi:[1,0,1]
	s_nop 0
	v_div_scale_f32 v5, s[2:3], v11, v11, v10
	v_rcp_f32_e32 v12, v5
	s_nop 0
	v_fma_f32 v13, -v5, v12, 1.0
	v_fmac_f32_e32 v12, v13, v12
	v_div_scale_f32 v13, vcc, v10, v11, v10
	v_mul_f32_e32 v14, v13, v12
	v_fma_f32 v15, -v5, v14, v13
	v_fmac_f32_e32 v14, v15, v12
	v_fma_f32 v5, -v5, v14, v13
	v_div_fmas_f32 v5, v5, v12, v14
	v_div_fixup_f32 v5, v5, v11, v10
	v_mul_f32_e32 v3, v5, v3
	v_cvt_pk_bf16_f32 v3, v3, s0
	v_lshl_add_u64 v[10:11], s[36:37], 0, v[20:21]
	v_cmp_gt_i32_e32 vcc, 2, v2
	global_store_short v[10:11], v3, off
	s_waitcnt vmcnt(1)
	v_lshlrev_b32_e32 v201, 16, v201
	v_lshlrev_b32_e32 v202, 16, v202
	v_lshlrev_b32_e32 v11, 16, v203
	v_lshlrev_b32_e32 v204, 16, v204
	v_lshlrev_b32_e32 v205, 16, v205
	v_cmp_lt_u32_e32 vcc, 1, v188
	v_mov_b32_e32 v8, v196
	v_mov_b32_e32 v9, v198
	v_cndmask_b32_e32 v10, v199, v201, vcc
	v_cmp_lt_u32_e32 vcc, 0, v188
	s_nop 1
	v_cndmask_b32_e32 v3, v200, v202, vcc
	v_pk_mul_f32 v[6:7], v[10:11], v[8:9]
	s_nop 0
	v_fma_f32 v2, v3, v197, v6
	v_add_f32_e32 v2, v2, v7
	v_mul_f32_e32 v2, v2, v204
	v_mul_f32_e32 v2, v2, v205
	v_cvt_pk_bf16_f32 v2, v2, s0
	global_store_short v193, v2, s[36:37]
	v_readlane_b32 s56, v247, 23
	v_readlane_b32 s57, v247, 24
	s_mov_b64 s[2:3], 0
	s_branch .LBB0_830
